# GLA output units: prefix-fold step issues its 20 loads together (one wait) instead of eight serialized load->wait->fma round trips
# speedup vs baseline: 1.0090x; 1.0090x over previous
.LBB0_448:
	s_or_b64 exec, exec, s[8:9]
	s_and_b64 s[8:9], s[44:45], exec
	v_readlane_b32 s8, v252, 43
	s_cselect_b32 s8, s67, s8
	s_cmp_gt_i32 s8, 0
	v_readlane_b32 s78, v252, 35
	s_cselect_b64 s[76:77], -1, 0
	v_readlane_b32 s79, v252, 36
	s_and_b64 s[76:77], s[78:79], s[76:77]
	v_mov_b32_e32 v22, 0
	s_andn2_b64 vcc, exec, s[76:77]
	v_mov_b32_e32 v23, 0
	v_mov_b32_e32 v24, 0
	v_mov_b32_e32 v25, 0
	v_mov_b32_e32 v26, 0
	v_mov_b32_e32 v27, 0
	v_mov_b32_e32 v28, 0
	v_mov_b32_e32 v29, 0
	v_mov_b32_e32 v30, 0
	v_mov_b32_e32 v31, 0
	v_mov_b32_e32 v32, 0
	v_mov_b32_e32 v33, 0
	v_mov_b32_e32 v38, 0
	v_mov_b32_e32 v39, 0
	v_mov_b32_e32 v40, 0
	v_mov_b32_e32 v41, 0
	s_waitcnt lgkmcnt(0)
	s_barrier
	s_cbranch_vccnz .LBB0_452
	s_or_b32 s9, s10, s61
	s_mov_b32 s10, 27
	s_ashr_i32 s11, s10, 31
	s_lshl_b64 s[10:11], s[10:11], 3
	s_add_u32 s10, s0, s10
	s_addc_u32 s11, s1, s11
	s_load_dwordx2 s[10:11], s[10:11], 0x0
	s_mul_i32 s76, s9, 17
	s_ashr_i32 s77, s76, 31
	s_lshl_b64 s[78:79], s[76:77], 15
	v_lshlrev_b32_e32 v2, 2, v106
	s_waitcnt lgkmcnt(0)
	s_add_u32 s9, s10, s78
	s_addc_u32 s11, s11, s79
	s_add_u32 s10, s9, s94
	s_mov_b32 s78, 27
	s_addc_u32 s11, s11, s95
	s_ashr_i32 s79, s78, 31
	s_lshl_b64 s[78:79], s[78:79], 3
	s_add_u32 s78, s0, s78
	s_addc_u32 s79, s1, s79
	s_load_dwordx2 s[78:79], s[78:79], 0x0
	s_lshl_b64 s[80:81], s[76:77], 8
	s_mov_b32 s55, 0x2400000
	s_waitcnt lgkmcnt(0)
	s_add_u32 s9, s78, s80
	s_addc_u32 s15, s79, s81
	s_add_u32 s78, s9, 0x3500000
	s_addc_u32 s79, s15, 0
	s_cmp_lt_u32 s8, 2
	v_lshlrev_b32_e32 v0, 2, v104
	v_lshlrev_b32_e32 v3, 2, v122
	v_lshl_add_u64 v[10:11], s[10:11], 0, v[0:1]
	v_lshl_add_u64 v[12:13], v[10:11], 0, s[86:87]
	v_add_co_u32_e32 v10, vcc, s55, v10
	s_nop 1
	v_addc_co_u32_e32 v11, vcc, 0, v11, vcc
	global_load_dword v42, v2, s[78:79]
	global_load_dword v44, v2, s[78:79] offset:64
	global_load_dword v46, v2, s[78:79] offset:128
	global_load_dword v48, v3, s[78:79]
	global_load_dword v50, v[10:11], off
	global_load_dword v51, v[12:13], off offset:256
	global_load_dword v52, v[12:13], off offset:512
	global_load_dword v53, v[12:13], off offset:768
	global_load_dword v54, v[12:13], off offset:1024
	global_load_dword v55, v[12:13], off offset:1280
	global_load_dword v56, v[12:13], off offset:1536
	global_load_dword v57, v[12:13], off offset:1792
	global_load_dword v58, v[12:13], off offset:2048
	global_load_dword v59, v[12:13], off offset:2304
	global_load_dword v60, v[12:13], off offset:2560
	global_load_dword v61, v[12:13], off offset:2816
	global_load_dword v62, v[12:13], off offset:3072
	global_load_dword v63, v[12:13], off offset:3328
	global_load_dword v64, v[12:13], off offset:3584
	global_load_dword v65, v[12:13], off offset:3840
	s_waitcnt vmcnt(0)
	v_mul_f32_e32 v8, 0, v42
	v_pk_add_f32 v[22:23], v[8:9], v[50:51] op_sel_hi:[0,1]
	v_pk_add_f32 v[24:25], v[8:9], v[52:53] op_sel_hi:[0,1]
	v_mul_f32_e32 v8, 0, v44
	v_pk_add_f32 v[26:27], v[8:9], v[54:55] op_sel_hi:[0,1]
	v_pk_add_f32 v[28:29], v[8:9], v[56:57] op_sel_hi:[0,1]
	v_mul_f32_e32 v8, 0, v46
	v_pk_add_f32 v[30:31], v[8:9], v[58:59] op_sel_hi:[0,1]
	v_pk_add_f32 v[32:33], v[8:9], v[60:61] op_sel_hi:[0,1]
	v_mul_f32_e32 v8, 0, v48
	v_pk_add_f32 v[38:39], v[8:9], v[62:63] op_sel_hi:[0,1]
	v_pk_add_f32 v[40:41], v[8:9], v[64:65] op_sel_hi:[0,1]
	s_cbranch_scc1 .LBB0_452
	s_mov_b32 s9, 1
	s_mov_b32 s10, 16
.LBB0_451:
	s_and_b64 s[78:79], s[44:45], exec
	s_mov_b32 s78, 27
	s_cselect_b32 s11, s9, s10
	s_ashr_i32 s79, s78, 31
	s_lshl_b64 s[78:79], s[78:79], 3
	s_add_u32 s78, s0, s78
	s_addc_u32 s79, s1, s79
	s_load_dwordx2 s[78:79], s[78:79], 0x0
	s_add_i32 s80, s11, s76
	s_ashr_i32 s81, s80, 31
	s_lshl_b64 s[82:83], s[80:81], 15
	s_waitcnt lgkmcnt(0)
	s_add_u32 s11, s78, s82
	s_addc_u32 s15, s79, s83
	s_add_u32 s78, s11, s94
	s_mov_b32 s82, 27
	s_addc_u32 s79, s15, s95
	s_ashr_i32 s83, s82, 31
	s_lshl_b64 s[82:83], s[82:83], 3
	s_add_u32 s82, s0, s82
	s_addc_u32 s83, s1, s83
	s_load_dwordx2 s[82:83], s[82:83], 0x0
	s_lshl_b64 s[80:81], s[80:81], 8
	v_lshl_add_u64 v[10:11], s[78:79], 0, v[0:1]
	v_lshl_add_u64 v[12:13], v[10:11], 0, s[86:87]
	v_add_co_u32_e32 v10, vcc, s55, v10
	s_waitcnt lgkmcnt(0)
	s_add_u32 s11, s82, s80
	s_addc_u32 s15, s83, s81
	s_add_u32 s80, s11, 0x3500000
	s_addc_u32 s81, s15, 0
	v_addc_co_u32_e32 v11, vcc, 0, v11, vcc
	global_load_dword v42, v2, s[80:81]
	global_load_dword v44, v2, s[80:81] offset:64
	global_load_dword v46, v2, s[80:81] offset:128
	global_load_dword v48, v3, s[80:81]
	global_load_dword v50, v[10:11], off
	global_load_dword v51, v[12:13], off offset:256
	global_load_dword v52, v[12:13], off offset:512
	global_load_dword v53, v[12:13], off offset:768
	global_load_dword v54, v[12:13], off offset:1024
	global_load_dword v55, v[12:13], off offset:1280
	global_load_dword v56, v[12:13], off offset:1536
	global_load_dword v57, v[12:13], off offset:1792
	global_load_dword v58, v[12:13], off offset:2048
	global_load_dword v59, v[12:13], off offset:2304
	global_load_dword v60, v[12:13], off offset:2560
	global_load_dword v61, v[12:13], off offset:2816
	global_load_dword v62, v[12:13], off offset:3072
	global_load_dword v63, v[12:13], off offset:3328
	global_load_dword v64, v[12:13], off offset:3584
	global_load_dword v65, v[12:13], off offset:3840
	s_add_i32 s9, s9, 1
	s_add_i32 s10, s10, -1
	s_cmp_eq_u32 s8, s9
	s_waitcnt vmcnt(0)
	v_pk_fma_f32 v[22:23], v[22:23], v[42:43], v[50:51] op_sel_hi:[1,0,1]
	v_pk_fma_f32 v[24:25], v[24:25], v[42:43], v[52:53] op_sel_hi:[1,0,1]
	v_pk_fma_f32 v[26:27], v[26:27], v[44:45], v[54:55] op_sel_hi:[1,0,1]
	v_pk_fma_f32 v[28:29], v[28:29], v[44:45], v[56:57] op_sel_hi:[1,0,1]
	v_pk_fma_f32 v[30:31], v[30:31], v[46:47], v[58:59] op_sel_hi:[1,0,1]
	v_pk_fma_f32 v[32:33], v[32:33], v[46:47], v[60:61] op_sel_hi:[1,0,1]
	v_pk_fma_f32 v[38:39], v[38:39], v[48:49], v[62:63] op_sel_hi:[1,0,1]
	v_pk_fma_f32 v[40:41], v[40:41], v[48:49], v[64:65] op_sel_hi:[1,0,1]
	s_cbranch_scc0 .LBB0_451
